# GEMM tile prologues: conservative vmcnt(0) drain relaxed to vmcnt(8) (only LDS-DMA stages 1-2 stay in flight; K-loop waits cover them), on top of v018
# speedup vs baseline: 1.0033x; 1.0033x over previous
.LBB0_96:
	s_and_b32 s8, s8, 0x1fc00
	s_sub_i32 s8, s11, s8
	v_and_b32_e32 v5, 63, v4
	s_lshr_b32 s18, s8, 8
	v_and_b32_e32 v6, 31, v4
	s_mul_i32 s18, s18, 0xb0000
	v_lshrrev_b32_e32 v5, 5, v5
	v_lshrrev_b32_e32 v7, 2, v4
	v_bfe_u32 v4, v4, 2, 2
	v_lshlrev_b32_e32 v8, 6, v6
	s_mul_i32 s7, s7, 0x16000
	v_lshl_or_b32 v8, s9, 13, v8
	s_and_b32 s9, s5, 0xc0
	v_bitop3_b32 v4, v5, v4, 2 bitop3:0x36
	s_add_i32 s7, s18, s7
	v_or_b32_e32 v6, s9, v6
	v_lshlrev_b32_e32 v204, 4, v4
	v_mov_b32_e32 v4, 0x4000
	s_add_i32 s7, s7, 0xb000
	s_and_b32 s8, s8, 0xffff00
	v_lshl_or_b32 v212, v6, 6, v4
	v_mov_b32_e32 v4, s7
	s_movk_i32 s2, 0xb00
	v_mad_u32_u24 v4, v2, s2, v4
	s_add_i32 s6, s6, s8
	v_or_b32_e32 v4, v4, v0
	v_add_u32_e32 v2, s6, v2
	v_bitop3_b32 v7, v5, v7, 3 bitop3:0x78
	v_ashrrev_i32_e32 v5, 31, v4
	v_mul_lo_u32 v2, v2, s2
	v_lshl_add_u64 v[180:181], v[4:5], 1, s[40:41]
	v_or_b32_e32 v4, v2, v0
	v_add_u32_e32 v2, v3, v0
	v_readlane_b32 s2, v253, 53
	v_lshlrev_b32_e32 v203, 4, v7
	v_ashrrev_i32_e32 v5, 31, v4
	v_ashrrev_i32_e32 v3, 31, v2
	v_readlane_b32 s3, v253, 54
	v_add_u32_e32 v176, v1, v0
	v_mov_b32_e32 v0, 0
	v_or_b32_e32 v211, v203, v8
	v_or_b32_e32 v214, v204, v8
	v_lshl_add_u64 v[182:183], v[4:5], 1, s[40:41]
	v_lshl_add_u64 v[184:185], v[2:3], 1, s[2:3]
	v_lshl_add_u64 v[186:187], v[176:177], 1, s[2:3]
	s_mov_b32 s18, 0
	s_mov_b64 s[6:7], 0
	s_mov_b32 s19, 0
	v_mov_b32_e32 v1, v0
	v_mov_b32_e32 v2, v0
	v_mov_b32_e32 v3, v0
	v_mov_b32_e32 v4, v0
	v_mov_b32_e32 v5, v0
	v_mov_b32_e32 v6, v0
	v_mov_b32_e32 v7, v0
	v_mov_b32_e32 v8, v0
	v_mov_b32_e32 v9, v0
	v_mov_b32_e32 v10, v0
	v_mov_b32_e32 v11, v0
	v_mov_b32_e32 v12, v0
	v_mov_b32_e32 v13, v0
	v_mov_b32_e32 v14, v0
	v_mov_b32_e32 v15, v0
	v_mov_b32_e32 v16, v0
	v_mov_b32_e32 v17, v0
	v_mov_b32_e32 v18, v0
	v_mov_b32_e32 v19, v0
	v_mov_b32_e32 v20, v0
	v_mov_b32_e32 v21, v0
	v_mov_b32_e32 v22, v0
	v_mov_b32_e32 v23, v0
	v_mov_b32_e32 v24, v0
	v_mov_b32_e32 v25, v0
	v_mov_b32_e32 v26, v0
	v_mov_b32_e32 v27, v0
	v_mov_b32_e32 v28, v0
	v_mov_b32_e32 v29, v0
	v_mov_b32_e32 v30, v0
	v_mov_b32_e32 v31, v0
	v_mov_b32_e32 v32, v0
	v_mov_b32_e32 v33, v0
	v_mov_b32_e32 v34, v0
	v_mov_b32_e32 v35, v0
	v_mov_b32_e32 v36, v0
	v_mov_b32_e32 v37, v0
	v_mov_b32_e32 v38, v0
	v_mov_b32_e32 v39, v0
	v_mov_b32_e32 v40, v0
	v_mov_b32_e32 v41, v0
	v_mov_b32_e32 v42, v0
	v_mov_b32_e32 v43, v0
	v_mov_b32_e32 v44, v0
	v_mov_b32_e32 v45, v0
	v_mov_b32_e32 v46, v0
	v_mov_b32_e32 v47, v0
	v_mov_b32_e32 v48, v0
	v_mov_b32_e32 v49, v0
	v_mov_b32_e32 v50, v0
	v_mov_b32_e32 v51, v0
	v_mov_b32_e32 v52, v0
	v_mov_b32_e32 v53, v0
	v_mov_b32_e32 v54, v0
	v_mov_b32_e32 v55, v0
	v_mov_b32_e32 v56, v0
	v_mov_b32_e32 v57, v0
	v_mov_b32_e32 v58, v0
	v_mov_b32_e32 v59, v0
	v_mov_b32_e32 v60, v0
	v_mov_b32_e32 v61, v0
	v_mov_b32_e32 v62, v0
	v_mov_b32_e32 v63, v0
	v_mov_b32_e32 v64, v0
	v_mov_b32_e32 v65, v0
	v_mov_b32_e32 v66, v0
	v_mov_b32_e32 v67, v0
	v_mov_b32_e32 v68, v0
	v_mov_b32_e32 v69, v0
	v_mov_b32_e32 v70, v0
	v_mov_b32_e32 v71, v0
	v_mov_b32_e32 v72, v0
	v_mov_b32_e32 v73, v0
	v_mov_b32_e32 v74, v0
	v_mov_b32_e32 v75, v0
	v_mov_b32_e32 v76, v0
	v_mov_b32_e32 v77, v0
	v_mov_b32_e32 v78, v0
	v_mov_b32_e32 v79, v0
	v_mov_b32_e32 v80, v0
	v_mov_b32_e32 v81, v0
	v_mov_b32_e32 v82, v0
	v_mov_b32_e32 v83, v0
	v_mov_b32_e32 v84, v0
	v_mov_b32_e32 v85, v0
	v_mov_b32_e32 v86, v0
	v_mov_b32_e32 v87, v0
	v_mov_b32_e32 v88, v0
	v_mov_b32_e32 v89, v0
	v_mov_b32_e32 v90, v0
	v_mov_b32_e32 v91, v0
	v_mov_b32_e32 v92, v0
	v_mov_b32_e32 v93, v0
	v_mov_b32_e32 v94, v0
	v_mov_b32_e32 v95, v0
	s_waitcnt vmcnt(8)
	v_mov_b32_e32 v96, v0
	v_mov_b32_e32 v97, v0
	v_mov_b32_e32 v98, v0
	v_mov_b32_e32 v99, v0
	v_mov_b32_e32 v100, v0
	v_mov_b32_e32 v101, v0
	v_mov_b32_e32 v102, v0
	v_mov_b32_e32 v103, v0
	v_mov_b32_e32 v104, v0
	v_mov_b32_e32 v105, v0
	v_mov_b32_e32 v106, v0
	v_mov_b32_e32 v107, v0
	v_mov_b32_e32 v108, v0
	v_mov_b32_e32 v109, v0
	v_mov_b32_e32 v110, v0
	v_mov_b32_e32 v111, v0
	v_mov_b32_e32 v112, v0
	v_mov_b32_e32 v113, v0
	v_mov_b32_e32 v114, v0
	v_mov_b32_e32 v115, v0
	v_mov_b32_e32 v116, v0
	v_mov_b32_e32 v117, v0
	v_mov_b32_e32 v118, v0
	v_mov_b32_e32 v119, v0
	v_mov_b32_e32 v120, v0
	v_mov_b32_e32 v121, v0
	v_mov_b32_e32 v122, v0
	v_mov_b32_e32 v123, v0
	v_mov_b32_e32 v124, v0
	v_mov_b32_e32 v125, v0
	v_mov_b32_e32 v126, v0
	v_mov_b32_e32 v127, v0
	s_branch .LBB0_98

.LBB0_121:
	v_and_b32_e32 v7, 63, v4
	v_and_b32_e32 v8, 31, v4
	v_lshrrev_b32_e32 v7, 5, v7
	v_lshrrev_b32_e32 v9, 2, v4
	v_bfe_u32 v4, v4, 2, 2
	v_lshlrev_b32_e32 v10, 6, v8
	v_lshl_or_b32 v10, s6, 13, v10
	s_and_b32 s6, s13, 0xc0
	v_bitop3_b32 v4, v7, v4, 2 bitop3:0x36
	v_or_b32_e32 v8, s6, v8
	v_lshlrev_b32_e32 v197, 4, v4
	v_mov_b32_e32 v4, 0x4000
	v_lshl_or_b32 v199, v8, 6, v4
	s_lshl_b32 s5, s5, 15
	v_add_u32_e32 v4, v6, v1
	v_lshl_add_u32 v4, v4, 10, s5
	v_or_b32_e32 v4, v4, v0
	v_add3_u32 v1, v5, v1, s4
	v_add_u32_e32 v6, 0x4000, v4
	v_lshl_or_b32 v4, v1, 10, v0
	v_ashrrev_i32_e32 v5, 31, v4
	v_lshl_add_u64 v[180:181], v[4:5], 1, s[62:63]
	v_add_u32_e32 v4, v3, v0
	v_readlane_b32 s2, v253, 57
	v_add_u32_e32 v0, v2, v0
	v_bitop3_b32 v9, v7, v9, 3 bitop3:0x78
	v_readlane_b32 s3, v253, 58
	v_ashrrev_i32_e32 v1, 31, v0
	v_lshlrev_b32_e32 v192, 4, v9
	v_ashrrev_i32_e32 v7, 31, v6
	v_ashrrev_i32_e32 v5, 31, v4
	v_lshl_add_u64 v[184:185], v[0:1], 1, s[2:3]
	v_mov_b32_e32 v0, 0
	v_or_b32_e32 v198, v192, v10
	v_or_b32_e32 v200, v197, v10
	v_lshl_add_u64 v[178:179], v[6:7], 1, s[62:63]
	v_lshl_add_u64 v[182:183], v[4:5], 1, s[2:3]
	s_mov_b32 s17, 0
	s_mov_b64 s[4:5], 0
	s_mov_b32 s18, 0
	v_mov_b32_e32 v1, v0
	v_mov_b32_e32 v2, v0
	v_mov_b32_e32 v3, v0
	v_mov_b32_e32 v4, v0
	v_mov_b32_e32 v5, v0
	v_mov_b32_e32 v6, v0
	v_mov_b32_e32 v7, v0
	v_mov_b32_e32 v8, v0
	v_mov_b32_e32 v9, v0
	v_mov_b32_e32 v10, v0
	v_mov_b32_e32 v11, v0
	v_mov_b32_e32 v12, v0
	v_mov_b32_e32 v13, v0
	v_mov_b32_e32 v14, v0
	v_mov_b32_e32 v15, v0
	v_mov_b32_e32 v16, v0
	v_mov_b32_e32 v17, v0
	v_mov_b32_e32 v18, v0
	v_mov_b32_e32 v19, v0
	v_mov_b32_e32 v20, v0
	v_mov_b32_e32 v21, v0
	v_mov_b32_e32 v22, v0
	v_mov_b32_e32 v23, v0
	v_mov_b32_e32 v24, v0
	v_mov_b32_e32 v25, v0
	v_mov_b32_e32 v26, v0
	v_mov_b32_e32 v27, v0
	v_mov_b32_e32 v28, v0
	v_mov_b32_e32 v29, v0
	v_mov_b32_e32 v30, v0
	v_mov_b32_e32 v31, v0
	v_mov_b32_e32 v32, v0
	v_mov_b32_e32 v33, v0
	v_mov_b32_e32 v34, v0
	v_mov_b32_e32 v35, v0
	v_mov_b32_e32 v36, v0
	v_mov_b32_e32 v37, v0
	v_mov_b32_e32 v38, v0
	v_mov_b32_e32 v39, v0
	v_mov_b32_e32 v40, v0
	v_mov_b32_e32 v41, v0
	v_mov_b32_e32 v42, v0
	v_mov_b32_e32 v43, v0
	v_mov_b32_e32 v44, v0
	v_mov_b32_e32 v45, v0
	v_mov_b32_e32 v46, v0
	v_mov_b32_e32 v47, v0
	v_mov_b32_e32 v48, v0
	v_mov_b32_e32 v49, v0
	v_mov_b32_e32 v50, v0
	v_mov_b32_e32 v51, v0
	v_mov_b32_e32 v52, v0
	v_mov_b32_e32 v53, v0
	v_mov_b32_e32 v54, v0
	v_mov_b32_e32 v55, v0
	v_mov_b32_e32 v56, v0
	v_mov_b32_e32 v57, v0
	v_mov_b32_e32 v58, v0
	v_mov_b32_e32 v59, v0
	v_mov_b32_e32 v60, v0
	v_mov_b32_e32 v61, v0
	v_mov_b32_e32 v62, v0
	v_mov_b32_e32 v63, v0
	v_mov_b32_e32 v64, v0
	v_mov_b32_e32 v65, v0
	v_mov_b32_e32 v66, v0
	v_mov_b32_e32 v67, v0
	v_mov_b32_e32 v68, v0
	v_mov_b32_e32 v69, v0
	v_mov_b32_e32 v70, v0
	v_mov_b32_e32 v71, v0
	v_mov_b32_e32 v72, v0
	v_mov_b32_e32 v73, v0
	v_mov_b32_e32 v74, v0
	v_mov_b32_e32 v75, v0
	v_mov_b32_e32 v76, v0
	v_mov_b32_e32 v77, v0
	v_mov_b32_e32 v78, v0
	v_mov_b32_e32 v79, v0
	v_mov_b32_e32 v80, v0
	v_mov_b32_e32 v81, v0
	v_mov_b32_e32 v82, v0
	v_mov_b32_e32 v83, v0
	v_mov_b32_e32 v84, v0
	v_mov_b32_e32 v85, v0
	v_mov_b32_e32 v86, v0
	v_mov_b32_e32 v87, v0
	v_mov_b32_e32 v88, v0
	v_mov_b32_e32 v89, v0
	v_mov_b32_e32 v90, v0
	v_mov_b32_e32 v91, v0
	v_mov_b32_e32 v92, v0
	v_mov_b32_e32 v93, v0
	v_mov_b32_e32 v94, v0
	v_mov_b32_e32 v95, v0
	s_waitcnt vmcnt(8)
	v_mov_b32_e32 v96, v0
	v_mov_b32_e32 v97, v0
	v_mov_b32_e32 v98, v0
	v_mov_b32_e32 v99, v0
	v_mov_b32_e32 v100, v0
	v_mov_b32_e32 v101, v0
	v_mov_b32_e32 v102, v0
	v_mov_b32_e32 v103, v0
	v_mov_b32_e32 v104, v0
	v_mov_b32_e32 v105, v0
	v_mov_b32_e32 v106, v0
	v_mov_b32_e32 v107, v0
	v_mov_b32_e32 v108, v0
	v_mov_b32_e32 v109, v0
	v_mov_b32_e32 v110, v0
	v_mov_b32_e32 v111, v0
	v_mov_b32_e32 v112, v0
	v_mov_b32_e32 v113, v0
	v_mov_b32_e32 v114, v0
	v_mov_b32_e32 v115, v0
	v_mov_b32_e32 v116, v0
	v_mov_b32_e32 v117, v0
	v_mov_b32_e32 v118, v0
	v_mov_b32_e32 v119, v0
	v_mov_b32_e32 v120, v0
	v_mov_b32_e32 v121, v0
	v_mov_b32_e32 v122, v0
	v_mov_b32_e32 v123, v0
	v_mov_b32_e32 v124, v0
	v_mov_b32_e32 v125, v0
	v_mov_b32_e32 v126, v0
	v_mov_b32_e32 v127, v0
	s_branch .LBB0_123

.LBB0_169:
	s_and_b32 s6, s6, 0x1fc00
	v_and_b32_e32 v5, 63, v4
	s_sub_i32 s17, s9, s6
	v_and_b32_e32 v6, 31, v4
	s_lshl_b32 s18, s17, 10
	v_lshrrev_b32_e32 v5, 5, v5
	v_lshrrev_b32_e32 v7, 2, v4
	v_bfe_u32 v4, v4, 2, 2
	v_lshlrev_b32_e32 v8, 6, v6
	s_and_b32 s18, s18, 0xfffc0000
	v_lshl_or_b32 v8, s7, 13, v8
	s_and_b32 s7, s14, 0xc0
	v_bitop3_b32 v4, v5, v4, 2 bitop3:0x36
	s_lshl_b32 s5, s5, 15
	v_or_b32_e32 v6, s7, v6
	v_lshlrev_b32_e32 v204, 4, v4
	v_mov_b32_e32 v4, 0x4000
	s_add_i32 s18, s18, s5
	v_lshl_or_b32 v212, v6, 6, v4
	v_lshl_or_b32 v4, v0, 10, s18
	s_and_b32 s17, s17, 0x3fff00
	v_or3_b32 v4, v4, v1, s20
	v_bitop3_b32 v7, v5, v7, 3 bitop3:0x78
	v_ashrrev_i32_e32 v5, 31, v4
	s_add_i32 s5, s4, s17
	v_lshl_add_u64 v[182:183], v[4:5], 1, s[44:45]
	v_add_u32_e32 v4, s5, v0
	v_lshl_or_b32 v4, v4, 10, v1
	s_add_i32 s4, s4, s6
	v_ashrrev_i32_e32 v5, 31, v4
	s_add_i32 s4, s4, s12
	v_lshl_add_u64 v[184:185], v[4:5], 1, s[44:45]
	v_add_u32_e32 v4, v3, v1
	v_add_u32_e32 v0, s4, v0
	v_mov_b32_e32 v1, 0x13fff
	v_readlane_b32 s2, v253, 53
	v_med3_i32 v0, v0, 0, v1
	v_lshlrev_b32_e32 v203, 4, v7
	v_ashrrev_i32_e32 v5, 31, v4
	v_readlane_b32 s3, v253, 54
	v_lshl_or_b32 v176, v0, 11, v2
	v_mov_b32_e32 v0, 0
	v_or_b32_e32 v211, v203, v8
	v_or_b32_e32 v214, v204, v8
	v_lshl_add_u64 v[186:187], v[4:5], 1, s[2:3]
	s_mov_b32 s17, 0
	v_lshl_add_u64 v[188:189], s[2:3], 0, v[176:177]
	s_mov_b64 s[4:5], 0
	s_mov_b32 s18, 0
	v_mov_b32_e32 v1, v0
	v_mov_b32_e32 v2, v0
	v_mov_b32_e32 v3, v0
	v_mov_b32_e32 v4, v0
	v_mov_b32_e32 v5, v0
	v_mov_b32_e32 v6, v0
	v_mov_b32_e32 v7, v0
	v_mov_b32_e32 v8, v0
	v_mov_b32_e32 v9, v0
	v_mov_b32_e32 v10, v0
	v_mov_b32_e32 v11, v0
	v_mov_b32_e32 v12, v0
	v_mov_b32_e32 v13, v0
	v_mov_b32_e32 v14, v0
	v_mov_b32_e32 v15, v0
	v_mov_b32_e32 v16, v0
	v_mov_b32_e32 v17, v0
	v_mov_b32_e32 v18, v0
	v_mov_b32_e32 v19, v0
	v_mov_b32_e32 v20, v0
	v_mov_b32_e32 v21, v0
	v_mov_b32_e32 v22, v0
	v_mov_b32_e32 v23, v0
	v_mov_b32_e32 v24, v0
	v_mov_b32_e32 v25, v0
	v_mov_b32_e32 v26, v0
	v_mov_b32_e32 v27, v0
	v_mov_b32_e32 v28, v0
	v_mov_b32_e32 v29, v0
	v_mov_b32_e32 v30, v0
	v_mov_b32_e32 v31, v0
	v_mov_b32_e32 v32, v0
	v_mov_b32_e32 v33, v0
	v_mov_b32_e32 v34, v0
	v_mov_b32_e32 v35, v0
	v_mov_b32_e32 v36, v0
	v_mov_b32_e32 v37, v0
	v_mov_b32_e32 v38, v0
	v_mov_b32_e32 v39, v0
	v_mov_b32_e32 v40, v0
	v_mov_b32_e32 v41, v0
	v_mov_b32_e32 v42, v0
	v_mov_b32_e32 v43, v0
	v_mov_b32_e32 v44, v0
	v_mov_b32_e32 v45, v0
	v_mov_b32_e32 v46, v0
	v_mov_b32_e32 v47, v0
	v_mov_b32_e32 v48, v0
	v_mov_b32_e32 v49, v0
	v_mov_b32_e32 v50, v0
	v_mov_b32_e32 v51, v0
	v_mov_b32_e32 v52, v0
	v_mov_b32_e32 v53, v0
	v_mov_b32_e32 v54, v0
	v_mov_b32_e32 v55, v0
	v_mov_b32_e32 v56, v0
	v_mov_b32_e32 v57, v0
	v_mov_b32_e32 v58, v0
	v_mov_b32_e32 v59, v0
	v_mov_b32_e32 v60, v0
	v_mov_b32_e32 v61, v0
	v_mov_b32_e32 v62, v0
	v_mov_b32_e32 v63, v0
	v_mov_b32_e32 v64, v0
	v_mov_b32_e32 v65, v0
	v_mov_b32_e32 v66, v0
	v_mov_b32_e32 v67, v0
	v_mov_b32_e32 v68, v0
	v_mov_b32_e32 v69, v0
	v_mov_b32_e32 v70, v0
	v_mov_b32_e32 v71, v0
	v_mov_b32_e32 v72, v0
	v_mov_b32_e32 v73, v0
	v_mov_b32_e32 v74, v0
	v_mov_b32_e32 v75, v0
	v_mov_b32_e32 v76, v0
	v_mov_b32_e32 v77, v0
	v_mov_b32_e32 v78, v0
	v_mov_b32_e32 v79, v0
	v_mov_b32_e32 v80, v0
	v_mov_b32_e32 v81, v0
	v_mov_b32_e32 v82, v0
	v_mov_b32_e32 v83, v0
	v_mov_b32_e32 v84, v0
	v_mov_b32_e32 v85, v0
	v_mov_b32_e32 v86, v0
	v_mov_b32_e32 v87, v0
	v_mov_b32_e32 v88, v0
	v_mov_b32_e32 v89, v0
	v_mov_b32_e32 v90, v0
	v_mov_b32_e32 v91, v0
	v_mov_b32_e32 v92, v0
	v_mov_b32_e32 v93, v0
	v_mov_b32_e32 v94, v0
	v_mov_b32_e32 v95, v0
	s_waitcnt vmcnt(8)
	v_mov_b32_e32 v96, v0
	v_mov_b32_e32 v97, v0
	v_mov_b32_e32 v98, v0
	v_mov_b32_e32 v99, v0
	v_mov_b32_e32 v100, v0
	v_mov_b32_e32 v101, v0
	v_mov_b32_e32 v102, v0
	v_mov_b32_e32 v103, v0
	v_mov_b32_e32 v104, v0
	v_mov_b32_e32 v105, v0
	v_mov_b32_e32 v106, v0
	v_mov_b32_e32 v107, v0
	v_mov_b32_e32 v108, v0
	v_mov_b32_e32 v109, v0
	v_mov_b32_e32 v110, v0
	v_mov_b32_e32 v111, v0
	v_mov_b32_e32 v112, v0
	v_mov_b32_e32 v113, v0
	v_mov_b32_e32 v114, v0
	v_mov_b32_e32 v115, v0
	v_mov_b32_e32 v116, v0
	v_mov_b32_e32 v117, v0
	v_mov_b32_e32 v118, v0
	v_mov_b32_e32 v119, v0
	v_mov_b32_e32 v120, v0
	v_mov_b32_e32 v121, v0
	v_mov_b32_e32 v122, v0
	v_mov_b32_e32 v123, v0
	v_mov_b32_e32 v124, v0
	v_mov_b32_e32 v125, v0
	v_mov_b32_e32 v126, v0
	v_mov_b32_e32 v127, v0
	s_branch .LBB0_171

.LBB0_293:
	v_and_b32_e32 v6, 31, v4
	v_and_b32_e32 v5, 63, v4
	v_lshlrev_b32_e32 v8, 6, v6
	v_lshrrev_b32_e32 v5, 5, v5
	v_lshrrev_b32_e32 v7, 2, v4
	v_bfe_u32 v4, v4, 2, 2
	v_lshl_or_b32 v8, s19, 13, v8
	s_and_b32 s19, s17, 0xc0
	v_or_b32_e32 v6, s19, v6
	v_bitop3_b32 v4, v5, v4, 2 bitop3:0x36
	s_lshl_b32 s19, s9, 18
	s_lshl_b32 s6, s6, 15
	v_lshlrev_b32_e32 v187, 4, v4
	v_mov_b32_e32 v4, 0x4000
	s_add_i32 s19, s19, s6
	v_lshl_or_b32 v189, v6, 6, v4
	v_lshl_or_b32 v4, v0, 10, s19
	s_mul_hi_u32 s7, s7, 0x5d1745e
	s_and_b32 s29, s13, 0x300
	v_or3_b32 v4, v4, v1, s20
	s_lshl_b32 s7, s7, 10
	v_bitop3_b32 v7, v5, v7, 3 bitop3:0x78
	v_ashrrev_i32_e32 v5, 31, v4
	s_add_i32 s5, s4, s5
	s_add_i32 s4, s4, s29
	v_lshl_add_u64 v[178:179], v[4:5], 1, s[46:47]
	v_add_u32_e32 v4, s5, v0
	s_add_i32 s4, s4, s7
	v_lshl_or_b32 v4, v4, 10, v1
	v_add_u32_e32 v176, v3, v1
	v_readlane_b32 s2, v253, 57
	v_add_u32_e32 v0, s4, v0
	v_mov_b32_e32 v1, 0x13fff
	v_readlane_b32 s3, v253, 58
	v_med3_i32 v0, v0, 0, v1
	v_lshlrev_b32_e32 v186, 4, v7
	v_ashrrev_i32_e32 v5, 31, v4
	v_lshl_add_u64 v[182:183], v[176:177], 1, s[2:3]
	v_lshl_or_b32 v176, v0, 11, v2
	v_mov_b32_e32 v0, 0
	v_or_b32_e32 v188, v186, v8
	v_or_b32_e32 v191, v187, v8
	v_lshl_add_u64 v[180:181], v[4:5], 1, s[46:47]
	s_mov_b32 s19, 0
	v_lshl_add_u64 v[184:185], s[2:3], 0, v[176:177]
	s_mov_b64 s[4:5], 0
	s_mov_b32 s29, 0
	v_mov_b32_e32 v1, v0
	v_mov_b32_e32 v2, v0
	v_mov_b32_e32 v3, v0
	v_mov_b32_e32 v4, v0
	v_mov_b32_e32 v5, v0
	v_mov_b32_e32 v6, v0
	v_mov_b32_e32 v7, v0
	v_mov_b32_e32 v8, v0
	v_mov_b32_e32 v9, v0
	v_mov_b32_e32 v10, v0
	v_mov_b32_e32 v11, v0
	v_mov_b32_e32 v12, v0
	v_mov_b32_e32 v13, v0
	v_mov_b32_e32 v14, v0
	v_mov_b32_e32 v15, v0
	v_mov_b32_e32 v16, v0
	v_mov_b32_e32 v17, v0
	v_mov_b32_e32 v18, v0
	v_mov_b32_e32 v19, v0
	v_mov_b32_e32 v20, v0
	v_mov_b32_e32 v21, v0
	v_mov_b32_e32 v22, v0
	v_mov_b32_e32 v23, v0
	v_mov_b32_e32 v24, v0
	v_mov_b32_e32 v25, v0
	v_mov_b32_e32 v26, v0
	v_mov_b32_e32 v27, v0
	v_mov_b32_e32 v28, v0
	v_mov_b32_e32 v29, v0
	v_mov_b32_e32 v30, v0
	v_mov_b32_e32 v31, v0
	v_mov_b32_e32 v32, v0
	v_mov_b32_e32 v33, v0
	v_mov_b32_e32 v34, v0
	v_mov_b32_e32 v35, v0
	v_mov_b32_e32 v36, v0
	v_mov_b32_e32 v37, v0
	v_mov_b32_e32 v38, v0
	v_mov_b32_e32 v39, v0
	v_mov_b32_e32 v40, v0
	v_mov_b32_e32 v41, v0
	v_mov_b32_e32 v42, v0
	v_mov_b32_e32 v43, v0
	v_mov_b32_e32 v44, v0
	v_mov_b32_e32 v45, v0
	v_mov_b32_e32 v46, v0
	v_mov_b32_e32 v47, v0
	v_mov_b32_e32 v48, v0
	v_mov_b32_e32 v49, v0
	v_mov_b32_e32 v50, v0
	v_mov_b32_e32 v51, v0
	v_mov_b32_e32 v52, v0
	v_mov_b32_e32 v53, v0
	v_mov_b32_e32 v54, v0
	v_mov_b32_e32 v55, v0
	v_mov_b32_e32 v56, v0
	v_mov_b32_e32 v57, v0
	v_mov_b32_e32 v58, v0
	v_mov_b32_e32 v59, v0
	v_mov_b32_e32 v60, v0
	v_mov_b32_e32 v61, v0
	v_mov_b32_e32 v62, v0
	v_mov_b32_e32 v63, v0
	v_mov_b32_e32 v64, v0
	v_mov_b32_e32 v65, v0
	v_mov_b32_e32 v66, v0
	v_mov_b32_e32 v67, v0
	v_mov_b32_e32 v68, v0
	v_mov_b32_e32 v69, v0
	v_mov_b32_e32 v70, v0
	v_mov_b32_e32 v71, v0
	v_mov_b32_e32 v72, v0
	v_mov_b32_e32 v73, v0
	v_mov_b32_e32 v74, v0
	v_mov_b32_e32 v75, v0
	v_mov_b32_e32 v76, v0
	v_mov_b32_e32 v77, v0
	v_mov_b32_e32 v78, v0
	v_mov_b32_e32 v79, v0
	v_mov_b32_e32 v80, v0
	v_mov_b32_e32 v81, v0
	v_mov_b32_e32 v82, v0
	v_mov_b32_e32 v83, v0
	v_mov_b32_e32 v84, v0
	v_mov_b32_e32 v85, v0
	v_mov_b32_e32 v86, v0
	v_mov_b32_e32 v87, v0
	v_mov_b32_e32 v88, v0
	v_mov_b32_e32 v89, v0
	v_mov_b32_e32 v90, v0
	v_mov_b32_e32 v91, v0
	v_mov_b32_e32 v92, v0
	v_mov_b32_e32 v93, v0
	v_mov_b32_e32 v94, v0
	v_mov_b32_e32 v95, v0
	s_waitcnt vmcnt(8)
	v_mov_b32_e32 v96, v0
	v_mov_b32_e32 v97, v0
	v_mov_b32_e32 v98, v0
	v_mov_b32_e32 v99, v0
	v_mov_b32_e32 v100, v0
	v_mov_b32_e32 v101, v0
	v_mov_b32_e32 v102, v0
	v_mov_b32_e32 v103, v0
	v_mov_b32_e32 v104, v0
	v_mov_b32_e32 v105, v0
	v_mov_b32_e32 v106, v0
	v_mov_b32_e32 v107, v0
	v_mov_b32_e32 v108, v0
	v_mov_b32_e32 v109, v0
	v_mov_b32_e32 v110, v0
	v_mov_b32_e32 v111, v0
	v_mov_b32_e32 v112, v0
	v_mov_b32_e32 v113, v0
	v_mov_b32_e32 v114, v0
	v_mov_b32_e32 v115, v0
	v_mov_b32_e32 v116, v0
	v_mov_b32_e32 v117, v0
	v_mov_b32_e32 v118, v0
	v_mov_b32_e32 v119, v0
	v_mov_b32_e32 v120, v0
	v_mov_b32_e32 v121, v0
	v_mov_b32_e32 v122, v0
	v_mov_b32_e32 v123, v0
	v_mov_b32_e32 v124, v0
	v_mov_b32_e32 v125, v0
	v_mov_b32_e32 v126, v0
	v_mov_b32_e32 v127, v0
	s_branch .LBB0_295
